# P9 cumsum rewritten as 3-row block scan on all 256 WGs (was 40 WGs serial); plus ss-hoist
# speedup vs baseline: 1.0231x; 1.0080x over previous
; #define LAS __attribute__((address_space(3)))
; template <int L, int C> __device__ __forceinline__ void cumsum_item(const float* src0, const float* src1, float* dst, LAS float* SEG, int hh, int seg) {
;     float s = 0.f;
; #pragma unroll 1
;     for (int c0 = 0; c0 < L; c0 += C) { float v[C];
; #pragma unroll
;         for (int i = 0; i < C; ++i) { const int t = seg * L + c0 + i; v[i] = (t < 2048) ? src0[(unsigned)(t * 16 + hh)] : src1[(unsigned)((t - 2048) * 16 + hh)]; }
; #pragma unroll
;         for (int i = 0; i < C; ++i) s += v[i]; }
;     SEG[seg * 16 + hh] = s;
; __device__ __forceinline__ void fox_cumsum(const Args& a, LAS unsigned char* lds, int vcu, int G) {
;     const int tid = threadIdx.x, hh = tid & 15, seg = tid >> 4;
;     LAS float* SEG = (LAS float*)lds;
;     for (int it = vcu; it < 40; it += G) {
;         const bool prompt = it < 8; const int b = prompt ? it : it - 8;
;         const float* src0 = prompt ? a.out + O_FLP + (size_t)b * 2048 * 16 : a.in[I_CLF] + (size_t)b * 2048 * 16;
;         const float* src1 = a.out + O_FLS + (size_t)b * 64 * 16;
;         if (prompt) cumsum_item<64, 32>(src0, src1, (float*)(a.ws + WS_CP) + (size_t)(b * 16 + hh) * 2048, SEG, hh, seg);
;         else cumsum_item<66, 22>(src0, src1, (float*)(a.ws + WS_CS) + (size_t)(b * 16 + hh) * 2112, SEG, hh, seg);
.LBB0_1546:
	s_cmp_lt_i32 s30, 10
	s_cselect_b64 s[10:11], -1, 0
	s_and_b64 s[0:1], s[10:11], s[0:1]
	s_andn2_b64 vcc, exec, s[0:1]
	s_cbranch_vccnz .LBB0_1582
	s_cmpk_eq_i32 s34, 0x100
	s_cbranch_scc0 .Lp9_orig
	v_readlane_b32 s40, v252, 6
	v_readlane_b32 s41, v252, 7
	v_lshlrev_b32_e32 v2, 8, v0
	v_lshlrev_b32_e32 v3, 4, v0
	v_and_b32_e32 v4, 63, v0
	v_lshlrev_b32_e32 v5, 6, v4
	v_lshlrev_b32_e32 v6, 2, v4
	v_lshl_add_u32 v7, v1, 8, v6
	v_add_u32_e32 v29, 0x2000, v6
	s_nop 2
	s_lshr_b32 s3, s96, 1
	s_lshr_b32 s14, s3, 4
	s_and_b32 s15, s3, 15
	s_lshl_b32 s14, s14, 17
	s_lshl_b32 s15, s15, 2
	s_add_u32 s14, s14, s15
	s_add_u32 s14, s14, 0xcc00000
	s_add_u32 s42, s40, s14
	s_addc_u32 s43, s41, 0
	s_lshl_b32 s14, s3, 13
	s_add_u32 s14, s14, 0x25800000
	s_add_u32 s44, s28, s14
	s_addc_u32 s45, s29, 0
	s_mov_b32 s3, s96
	s_lshr_b32 s14, s3, 4
	s_and_b32 s15, s3, 15
	s_lshl_b32 s15, s15, 2
	s_lshl_b32 s38, s14, 17
	s_add_u32 s38, s38, s15
	s_add_u32 s46, s22, s38
	s_addc_u32 s47, s23, 0
	s_lshl_b32 s38, s14, 12
	s_add_u32 s38, s38, s15
	s_add_u32 s38, s38, 0xed00000
	s_add_u32 s48, s40, s38
	s_addc_u32 s49, s41, 0
	s_mul_i32 s38, s3, 0x2100
	s_add_u32 s38, s38, 0x25900000
	s_add_u32 s50, s28, s38
	s_addc_u32 s51, s29, 0
	s_add_u32 s3, s96, 0x100
	s_lshr_b32 s14, s3, 4
	s_and_b32 s15, s3, 15
	s_lshl_b32 s15, s15, 2
	s_lshl_b32 s38, s14, 17
	s_add_u32 s38, s38, s15
	s_add_u32 s52, s22, s38
	s_addc_u32 s53, s23, 0
	s_lshl_b32 s38, s14, 12
	s_add_u32 s38, s38, s15
	s_add_u32 s38, s38, 0xed00000
	s_add_u32 s54, s40, s38
	s_addc_u32 s55, s41, 0
	s_mul_i32 s38, s3, 0x2100
	s_add_u32 s38, s38, 0x25900000
	s_add_u32 s60, s28, s38
	s_addc_u32 s61, s29, 0
	global_load_dword v10, v2, s[42:43]
	global_load_dword v11, v2, s[42:43] offset:64
	global_load_dword v12, v2, s[42:43] offset:128
	global_load_dword v13, v2, s[42:43] offset:192
	global_load_dword v14, v2, s[46:47]
	global_load_dword v15, v2, s[46:47] offset:64
	global_load_dword v16, v2, s[46:47] offset:128
	global_load_dword v17, v2, s[46:47] offset:192
	global_load_dword v22, v5, s[48:49]
	global_load_dword v18, v2, s[52:53]
	global_load_dword v19, v2, s[52:53] offset:64
	global_load_dword v20, v2, s[52:53] offset:128
	global_load_dword v21, v2, s[52:53] offset:192
	global_load_dword v23, v5, s[54:55]
	s_waitcnt vmcnt(10)
	v_add_f32_e32 v11, v10, v11
	v_add_f32_e32 v12, v11, v12
	v_add_f32_e32 v13, v12, v13
	v_mov_b32_e32 v24, v13
	s_nop 1
	v_add_f32_dpp v24, v24, v24 row_shr:1 row_mask:0xf bank_mask:0xf
	s_nop 1
	v_add_f32_dpp v24, v24, v24 row_shr:2 row_mask:0xf bank_mask:0xf
	s_nop 1
	v_add_f32_dpp v24, v24, v24 row_shr:4 row_mask:0xf bank_mask:0xf
	s_nop 1
	v_add_f32_dpp v24, v24, v24 row_shr:8 row_mask:0xf bank_mask:0xf
	s_nop 1
	v_add_f32_dpp v24, v24, v24 row_bcast:15 row_mask:0xa bank_mask:0xf
	s_nop 1
	v_add_f32_dpp v24, v24, v24 row_bcast:31 row_mask:0xc bank_mask:0xf
	ds_write_b32 v7, v24 offset:0
	s_waitcnt vmcnt(5)
	v_add_f32_e32 v15, v14, v15
	v_add_f32_e32 v16, v15, v16
	v_add_f32_e32 v17, v16, v17
	v_mov_b32_e32 v25, v17
	s_nop 1
	v_add_f32_dpp v25, v25, v25 row_shr:1 row_mask:0xf bank_mask:0xf
	s_nop 1
	v_add_f32_dpp v25, v25, v25 row_shr:2 row_mask:0xf bank_mask:0xf
	s_nop 1
	v_add_f32_dpp v25, v25, v25 row_shr:4 row_mask:0xf bank_mask:0xf
	s_nop 1
	v_add_f32_dpp v25, v25, v25 row_shr:8 row_mask:0xf bank_mask:0xf
	s_nop 1
	v_add_f32_dpp v25, v25, v25 row_bcast:15 row_mask:0xa bank_mask:0xf
	s_nop 1
	v_add_f32_dpp v25, v25, v25 row_bcast:31 row_mask:0xc bank_mask:0xf
	s_nop 1
	v_add_f32_dpp v22, v22, v22 row_shr:1 row_mask:0xf bank_mask:0xf
	s_nop 1
	v_add_f32_dpp v22, v22, v22 row_shr:2 row_mask:0xf bank_mask:0xf
	s_nop 1
	v_add_f32_dpp v22, v22, v22 row_shr:4 row_mask:0xf bank_mask:0xf
	s_nop 1
	v_add_f32_dpp v22, v22, v22 row_shr:8 row_mask:0xf bank_mask:0xf
	s_nop 1
	v_add_f32_dpp v22, v22, v22 row_bcast:15 row_mask:0xa bank_mask:0xf
	s_nop 1
	v_add_f32_dpp v22, v22, v22 row_bcast:31 row_mask:0xc bank_mask:0xf
	ds_write_b32 v7, v25 offset:2048
	s_waitcnt vmcnt(0)
	v_add_f32_e32 v19, v18, v19
	v_add_f32_e32 v20, v19, v20
	v_add_f32_e32 v21, v20, v21
	v_mov_b32_e32 v26, v21
	s_nop 1
	v_add_f32_dpp v26, v26, v26 row_shr:1 row_mask:0xf bank_mask:0xf
	s_nop 1
	v_add_f32_dpp v26, v26, v26 row_shr:2 row_mask:0xf bank_mask:0xf
	s_nop 1
	v_add_f32_dpp v26, v26, v26 row_shr:4 row_mask:0xf bank_mask:0xf
	s_nop 1
	v_add_f32_dpp v26, v26, v26 row_shr:8 row_mask:0xf bank_mask:0xf
	s_nop 1
	v_add_f32_dpp v26, v26, v26 row_bcast:15 row_mask:0xa bank_mask:0xf
	s_nop 1
	v_add_f32_dpp v26, v26, v26 row_bcast:31 row_mask:0xc bank_mask:0xf
	s_nop 1
	v_add_f32_dpp v23, v23, v23 row_shr:1 row_mask:0xf bank_mask:0xf
	s_nop 1
	v_add_f32_dpp v23, v23, v23 row_shr:2 row_mask:0xf bank_mask:0xf
	s_nop 1
	v_add_f32_dpp v23, v23, v23 row_shr:4 row_mask:0xf bank_mask:0xf
	s_nop 1
	v_add_f32_dpp v23, v23, v23 row_shr:8 row_mask:0xf bank_mask:0xf
	s_nop 1
	v_add_f32_dpp v23, v23, v23 row_bcast:15 row_mask:0xa bank_mask:0xf
	s_nop 1
	v_add_f32_dpp v23, v23, v23 row_bcast:31 row_mask:0xc bank_mask:0xf
	ds_write_b32 v7, v26 offset:4096
	s_waitcnt lgkmcnt(0)
	s_barrier
; #define LAS __attribute__((address_space(3)))
; template <int L, int C> __device__ __forceinline__ void cumsum_item(const float* src0, const float* src1, float* dst, LAS float* SEG, int hh, int seg) {
;     ...
;     __syncthreads();
;     float run = 0.f;
;     for (int g = 0; g < seg; ++g) run += SEG[g * 16 + hh];
; #pragma unroll 1
;     for (int c0 = 0; c0 < L; c0 += C) { float v[C];
; #pragma unroll
;         for (int i = 0; i < C; ++i) { const int t = seg * L + c0 + i; v[i] = (t < 2048) ? src0[(unsigned)(t * 16 + hh)] : src1[(unsigned)((t - 2048) * 16 + hh)]; }
; #pragma unroll
;         for (int i = 0; i < C; ++i) { run += v[i]; dst[seg * L + c0 + i] = run; } }
;     __syncthreads();
; }
; __device__ __forceinline__ void fox_cumsum(const Args& a, LAS unsigned char* lds, int vcu, int G) {
;     const int tid = threadIdx.x, hh = tid & 15, seg = tid >> 4;
;     LAS float* SEG = (LAS float*)lds;
;     for (int it = vcu; it < 40; it += G) {
;         const bool prompt = it < 8; const int b = prompt ? it : it - 8;
;         const float* src0 = prompt ? a.out + O_FLP + (size_t)b * 2048 * 16 : a.in[I_CLF] + (size_t)b * 2048 * 16;
;         const float* src1 = a.out + O_FLS + (size_t)b * 64 * 16;
;         if (prompt) cumsum_item<64, 32>(src0, src1, (float*)(a.ws + WS_CP) + (size_t)(b * 16 + hh) * 2048, SEG, hh, seg);
;         else cumsum_item<66, 22>(src0, src1, (float*)(a.ws + WS_CS) + (size_t)(b * 16 + hh) * 2112, SEG, hh, seg);
	v_mov_b32_e32 v8, 0
	ds_read_b32 v30, v8 offset:252
	ds_read_b32 v31, v8 offset:508
	ds_read_b32 v32, v8 offset:764
	ds_read_b32 v33, v8 offset:1020
	ds_read_b32 v34, v8 offset:1276
	ds_read_b32 v35, v8 offset:1532
	ds_read_b32 v36, v8 offset:1788
	ds_read_b32 v37, v8 offset:2044
	ds_read_b32 v38, v8 offset:2300
	ds_read_b32 v39, v8 offset:2556
	ds_read_b32 v40, v8 offset:2812
	ds_read_b32 v41, v8 offset:3068
	ds_read_b32 v42, v8 offset:3324
	ds_read_b32 v43, v8 offset:3580
	ds_read_b32 v44, v8 offset:3836
	ds_read_b32 v45, v8 offset:4092
	ds_read_b32 v46, v8 offset:4348
	ds_read_b32 v47, v8 offset:4604
	ds_read_b32 v48, v8 offset:4860
	ds_read_b32 v49, v8 offset:5116
	ds_read_b32 v50, v8 offset:5372
	ds_read_b32 v51, v8 offset:5628
	ds_read_b32 v52, v8 offset:5884
	ds_read_b32 v53, v8 offset:6140
	s_waitcnt lgkmcnt(0)
	v_sub_f32_e32 v24, v24, v13
	v_mov_b32_e32 v9, 0
	v_cmp_lt_u32_e32 vcc, 0, v1
	s_nop 1
	v_cndmask_b32_e32 v27, 0, v30, vcc
	v_add_f32_e32 v9, v9, v27
	v_cmp_lt_u32_e32 vcc, 1, v1
	s_nop 1
	v_cndmask_b32_e32 v27, 0, v31, vcc
	v_add_f32_e32 v9, v9, v27
	v_cmp_lt_u32_e32 vcc, 2, v1
	s_nop 1
	v_cndmask_b32_e32 v27, 0, v32, vcc
	v_add_f32_e32 v9, v9, v27
	v_cmp_lt_u32_e32 vcc, 3, v1
	s_nop 1
	v_cndmask_b32_e32 v27, 0, v33, vcc
	v_add_f32_e32 v9, v9, v27
	v_cmp_lt_u32_e32 vcc, 4, v1
	s_nop 1
	v_cndmask_b32_e32 v27, 0, v34, vcc
	v_add_f32_e32 v9, v9, v27
	v_cmp_lt_u32_e32 vcc, 5, v1
	s_nop 1
	v_cndmask_b32_e32 v27, 0, v35, vcc
	v_add_f32_e32 v9, v9, v27
	v_cmp_lt_u32_e32 vcc, 6, v1
	s_nop 1
	v_cndmask_b32_e32 v27, 0, v36, vcc
	v_add_f32_e32 v9, v9, v27
	v_add_f32_e32 v24, v24, v9
	v_add_f32_e32 v10, v10, v24
	v_add_f32_e32 v11, v11, v24
	v_add_f32_e32 v12, v12, v24
	v_add_f32_e32 v13, v13, v24
	global_store_dwordx4 v3, v[10:13], s[44:45]
	v_sub_f32_e32 v25, v25, v17
	v_mov_b32_e32 v9, 0
	v_cmp_lt_u32_e32 vcc, 0, v1
	s_nop 1
	v_cndmask_b32_e32 v27, 0, v38, vcc
	v_add_f32_e32 v9, v9, v27
	v_cmp_lt_u32_e32 vcc, 1, v1
	s_nop 1
	v_cndmask_b32_e32 v27, 0, v39, vcc
	v_add_f32_e32 v9, v9, v27
	v_cmp_lt_u32_e32 vcc, 2, v1
	s_nop 1
	v_cndmask_b32_e32 v27, 0, v40, vcc
	v_add_f32_e32 v9, v9, v27
	v_cmp_lt_u32_e32 vcc, 3, v1
	s_nop 1
	v_cndmask_b32_e32 v27, 0, v41, vcc
	v_add_f32_e32 v9, v9, v27
	v_cmp_lt_u32_e32 vcc, 4, v1
	s_nop 1
	v_cndmask_b32_e32 v27, 0, v42, vcc
	v_add_f32_e32 v9, v9, v27
	v_cmp_lt_u32_e32 vcc, 5, v1
	s_nop 1
	v_cndmask_b32_e32 v27, 0, v43, vcc
	v_add_f32_e32 v9, v9, v27
	v_cmp_lt_u32_e32 vcc, 6, v1
	s_nop 1
	v_cndmask_b32_e32 v27, 0, v44, vcc
	v_add_f32_e32 v9, v9, v27
	v_add_f32_e32 v25, v25, v9
	v_add_f32_e32 v14, v14, v25
	v_add_f32_e32 v15, v15, v25
	v_add_f32_e32 v16, v16, v25
	v_add_f32_e32 v17, v17, v25
	global_store_dwordx4 v3, v[14:17], s[50:51]
	v_add_f32_e32 v28, v38, v39
	v_add_f32_e32 v28, v28, v40
	v_add_f32_e32 v28, v28, v41
	v_add_f32_e32 v28, v28, v42
	v_add_f32_e32 v28, v28, v43
	v_add_f32_e32 v28, v28, v44
	v_add_f32_e32 v28, v28, v45
	v_add_f32_e32 v22, v22, v28
	global_store_dword v29, v22, s[50:51]
	v_sub_f32_e32 v26, v26, v21
	v_mov_b32_e32 v9, 0
	v_cmp_lt_u32_e32 vcc, 0, v1
	s_nop 1
	v_cndmask_b32_e32 v27, 0, v46, vcc
	v_add_f32_e32 v9, v9, v27
	v_cmp_lt_u32_e32 vcc, 1, v1
	s_nop 1
	v_cndmask_b32_e32 v27, 0, v47, vcc
	v_add_f32_e32 v9, v9, v27
	v_cmp_lt_u32_e32 vcc, 2, v1
	s_nop 1
	v_cndmask_b32_e32 v27, 0, v48, vcc
	v_add_f32_e32 v9, v9, v27
	v_cmp_lt_u32_e32 vcc, 3, v1
	s_nop 1
	v_cndmask_b32_e32 v27, 0, v49, vcc
	v_add_f32_e32 v9, v9, v27
	v_cmp_lt_u32_e32 vcc, 4, v1
	s_nop 1
	v_cndmask_b32_e32 v27, 0, v50, vcc
	v_add_f32_e32 v9, v9, v27
	v_cmp_lt_u32_e32 vcc, 5, v1
	s_nop 1
	v_cndmask_b32_e32 v27, 0, v51, vcc
	v_add_f32_e32 v9, v9, v27
	v_cmp_lt_u32_e32 vcc, 6, v1
	s_nop 1
	v_cndmask_b32_e32 v27, 0, v52, vcc
	v_add_f32_e32 v9, v9, v27
	v_add_f32_e32 v26, v26, v9
	v_add_f32_e32 v18, v18, v26
	v_add_f32_e32 v19, v19, v26
	v_add_f32_e32 v20, v20, v26
	v_add_f32_e32 v21, v21, v26
	global_store_dwordx4 v3, v[18:21], s[60:61]
	v_add_f32_e32 v28, v46, v47
	v_add_f32_e32 v28, v28, v48
	v_add_f32_e32 v28, v28, v49
	v_add_f32_e32 v28, v28, v50
	v_add_f32_e32 v28, v28, v51
	v_add_f32_e32 v28, v28, v52
	v_add_f32_e32 v28, v28, v53
	v_add_f32_e32 v23, v23, v28
	global_store_dword v29, v23, s[60:61]
	s_branch .LBB0_1582
.Lp9_orig:
	s_cmp_gt_i32 s96, 39
	s_cbranch_scc1 .LBB0_1582
	v_readlane_b32 s40, v252, 0
	v_readlane_b32 s41, v252, 1
	v_readlane_b32 s42, v252, 2
	v_readlane_b32 s43, v252, 3
	v_readlane_b32 s44, v252, 4
	v_readlane_b32 s45, v252, 5
	v_readlane_b32 s46, v252, 6
	v_readlane_b32 s47, v252, 7
	s_mov_b64 s[40:41], s[44:45]
	s_movk_i32 s3, 0x200
	s_mov_b64 s[42:43], s[46:47]
	v_lshrrev_b32_e32 v2, 4, v0
	v_cmp_gt_u32_e64 s[4:5], s3, v0
	s_add_u32 s3, s42, 0xed00000
	v_mul_u32_u24_e32 v15, 0x42, v2
	s_addc_u32 s35, s43, 0
	v_lshlrev_b32_e32 v17, 6, v2
	s_add_u32 s44, s42, 0xcc00000
	s_waitcnt lgkmcnt(0)
	v_add_u32_e32 v3, -1, v2
	v_and_b32_e32 v19, 24, v2
	v_lshl_or_b32 v2, v15, 4, v170
	v_lshlrev_b32_e32 v6, 2, v15
	v_mov_b32_e32 v7, 0
	s_addc_u32 s45, s43, 0
	v_cmp_lt_u32_e64 s[6:7], 6, v3
	v_add_u32_e32 v20, 0x150, v2
	v_lshl_add_u64 v[2:3], s[28:29], 0, v[6:7]
	s_mov_b64 s[24:25], 0x25900054
	v_lshl_add_u32 v14, v170, 2, 0
	s_add_u32 s14, s28, 0x25800000
	v_bfe_u32 v18, v0, 4, 3
	v_lshl_add_u64 v[8:9], v[2:3], 0, s[24:25]
	v_lshl_or_b32 v2, s96, 4, v170
	v_or_b32_e32 v16, 0xffff8000, v170
	v_cmp_lt_u32_e64 s[0:1], 15, v0
	s_addc_u32 s15, s29, 0
	v_cmp_ne_u32_e64 s[8:9], 0, v18
	v_add_u32_e32 v21, 0xffffff80, v2
	s_lshl_b32 s46, s34, 4
	s_movk_i32 s47, 0x800
	s_movk_i32 s48, 0x7fe
	s_movk_i32 s49, 0x7fd
	s_movk_i32 s50, 0x7fc
	s_movk_i32 s51, 0x7fb
	s_movk_i32 s52, 0x7fa
	s_movk_i32 s53, 0x7f9
	s_movk_i32 s54, 0x7f8
	s_movk_i32 s55, 0x7f7
	s_movk_i32 s60, 0x7f6
	s_movk_i32 s61, 0x7f5
	s_movk_i32 s62, 0x7f4
	s_movk_i32 s63, 0x7f3
	s_movk_i32 s66, 0x7f2
	s_movk_i32 s67, 0x7f1
	s_movk_i32 s68, 0x7f0
	s_movk_i32 s69, 0x7ef
	s_movk_i32 s70, 0x7ee
	s_movk_i32 s71, 0x7ed
	s_movk_i32 s72, 0x7ec
	s_movk_i32 s73, 0x7eb
	v_add_u32_e32 v22, v14, v17
	s_movk_i32 s74, 0x2100
	s_mov_b64 s[24:25], 0x58
	s_mov_b32 s75, s96
	s_branch .LBB0_1550
